# baseline (speedup 1.0000x reference)
.LBB0_224:
	v_ashrrev_i32_e32 v138, 5, v158
	v_add_u32_e32 v139, s91, v138
	v_mov_b64_e32 v[150:151], s[92:93]
	v_mad_u64_u32 v[142:143], s[0:1], v139, s47, v[150:151]
	v_ashrrev_i32_e32 v141, 31, v139
	v_mov_b32_e32 v144, v143
	v_mad_u64_u32 v[144:145], s[0:1], v141, s47, v[144:145]
	v_lshlrev_b32_e32 v128, 4, v158
	v_mov_b32_e32 v143, v144
	v_and_b32_e32 v128, 0x1f0, v128
	v_mul_lo_u32 v137, v138, s49
	v_lshl_add_u64 v[142:143], v[142:143], 1, s[96:97]
	v_add_u32_e32 v139, 16, v138
	v_cvt_pk_bf16_f32 v130, v130, v131
	v_cvt_pk_bf16_f32 v131, v132, v133
	v_add_u32_e32 v140, v128, v137
	v_lshl_add_u64 v[142:143], v[142:143], 0, v[128:129]
	v_add_u32_e32 v141, s91, v139
	ds_write_b64 v136, v[130:131] offset:25632
	s_waitcnt lgkmcnt(0)
	s_barrier
	ds_read_b128 v[130:133], v140
	s_waitcnt lgkmcnt(0)
	global_store_dwordx4 v[142:143], v[130:133], off
	s_nop 1
	v_mad_u64_u32 v[142:143], s[0:1], v141, s47, v[150:151]
	v_ashrrev_i32_e32 v145, 31, v141
	v_mov_b32_e32 v144, v143
	v_mad_u64_u32 v[144:145], s[0:1], v145, s47, v[144:145]
	v_mov_b32_e32 v143, v144
	v_add_u32_e32 v130, 0x2100, v137
	v_lshl_add_u64 v[142:143], v[142:143], 1, s[96:97]
	v_add_u32_e32 v137, v128, v130
	v_lshl_add_u64 v[142:143], v[142:143], 0, v[128:129]
	v_add_u32_e32 v141, 32, v138
	ds_read_b128 v[130:133], v137
	s_waitcnt lgkmcnt(0)
	global_store_dwordx4 v[142:143], v[130:133], off
	s_nop 1
	v_add_u32_e32 v142, s91, v141
	v_ashrrev_i32_e32 v145, 31, v142
	v_mad_u64_u32 v[142:143], s[0:1], v142, s47, v[150:151]
	v_mov_b32_e32 v144, v143
	v_mad_u64_u32 v[144:145], s[0:1], v145, s47, v[144:145]
	v_mov_b32_e32 v143, v144
	v_lshl_add_u64 v[142:143], v[142:143], 1, s[96:97]
	v_lshl_add_u64 v[142:143], v[142:143], 0, v[128:129]
	ds_read_b128 v[130:133], v137 offset:8448
	s_waitcnt lgkmcnt(0)
	global_store_dwordx4 v[142:143], v[130:133], off
	s_nop 1
	v_add_u32_e32 v142, 48, v138
	v_add_u32_e32 v143, s91, v142
	v_mad_u64_u32 v[144:145], s[0:1], v143, s47, v[150:151]
	v_ashrrev_i32_e32 v161, 31, v143
	v_mov_b32_e32 v146, v145
	v_mad_u64_u32 v[162:163], s[0:1], v161, s47, v[146:147]
	v_mov_b32_e32 v145, v162
	v_lshl_add_u64 v[144:145], v[144:145], 1, s[96:97]
	v_lshl_add_u64 v[144:145], v[144:145], 0, v[128:129]
	v_add_u32_e32 v143, 64, v138
	ds_read_b128 v[130:133], v137 offset:16896
	s_waitcnt lgkmcnt(0)
	global_store_dwordx4 v[144:145], v[130:133], off
	s_nop 1
	v_add_u32_e32 v144, s91, v143
	v_ashrrev_i32_e32 v161, 31, v144
	v_mad_u64_u32 v[144:145], s[0:1], v144, s47, v[150:151]
	v_mov_b32_e32 v146, v145
	v_mad_u64_u32 v[162:163], s[0:1], v161, s47, v[146:147]
	v_mov_b32_e32 v145, v162
	v_lshl_add_u64 v[144:145], v[144:145], 1, s[96:97]
	v_lshl_add_u64 v[144:145], v[144:145], 0, v[128:129]
	ds_read_b128 v[130:133], v137 offset:25344
	s_waitcnt lgkmcnt(0)
	global_store_dwordx4 v[144:145], v[130:133], off
	s_nop 1
	v_add_u32_e32 v144, 0x50, v138
	v_add_u32_e32 v145, s91, v144
	v_mad_u64_u32 v[162:163], s[0:1], v145, s47, v[150:151]
	v_ashrrev_i32_e32 v161, 31, v145
	v_mov_b32_e32 v146, v163
	v_mad_u64_u32 v[164:165], s[0:1], v161, s47, v[146:147]
	v_mov_b32_e32 v163, v164
	v_lshl_add_u64 v[162:163], v[162:163], 1, s[96:97]
	v_add_u32_e32 v145, 0x60, v138
	v_lshl_add_u64 v[162:163], v[162:163], 0, v[128:129]
	v_add_u32_e32 v146, s91, v145
	ds_read_b128 v[130:133], v137 offset:33792
	s_waitcnt lgkmcnt(0)
	global_store_dwordx4 v[162:163], v[130:133], off
	s_nop 1
	v_mad_u64_u32 v[162:163], s[0:1], v146, s47, v[150:151]
	v_ashrrev_i32_e32 v161, 31, v146
	v_mov_b32_e32 v146, v163
	v_mad_u64_u32 v[164:165], s[0:1], v161, s47, v[146:147]
	v_mov_b32_e32 v163, v164
	v_add_u32_e32 v146, 0x70, v138
	v_lshl_add_u64 v[162:163], v[162:163], 1, s[96:97]
	v_add_u32_e32 v161, s91, v146
	v_lshl_add_u64 v[162:163], v[162:163], 0, v[128:129]
	v_mad_u64_u32 v[150:151], s[0:1], v161, s47, v[150:151]
	ds_read_b128 v[130:133], v137 offset:42240
	s_waitcnt lgkmcnt(0)
	global_store_dwordx4 v[162:163], v[130:133], off
	s_nop 1
	v_ashrrev_i32_e32 v163, 31, v161
	v_mov_b32_e32 v162, v151
	v_mad_u64_u32 v[162:163], s[0:1], v163, s47, v[162:163]
	v_mov_b32_e32 v151, v162
	v_lshl_add_u64 v[150:151], v[150:151], 1, s[96:97]
	ds_read_b128 v[130:133], v137 offset:50688
	v_lshl_add_u64 v[150:151], v[150:151], 0, v[128:129]
	s_waitcnt lgkmcnt(0)
	global_store_dwordx4 v[150:151], v[130:133], off
	s_nop 1
	s_and_b64 vcc, exec, s[4:5]
	v_mov_b32_e32 v130, v60
	v_mov_b32_e32 v131, v61
	v_mov_b32_e32 v132, v62
	v_mov_b32_e32 v133, v63
	s_barrier
	s_cbranch_vccnz .LBB0_226
	v_max_f32_e32 v130, v60, v60
	v_max_f32_e32 v131, v61, v61
	v_max_f32_e32 v132, v62, v62
	v_max_f32_e32 v133, v63, v63
	v_max_f32_e32 v130, 0, v130
	v_max_f32_e32 v131, 0, v131
	v_max_f32_e32 v132, 0, v132
	v_max_f32_e32 v133, 0, v133
	v_pk_mul_f32 v[130:131], v[130:131], v[130:131]
	v_pk_mul_f32 v[132:133], v[132:133], v[132:133]

.LBB0_256:
	v_cvt_pk_bf16_f32 v132, v132, v133
	s_nop 0
	v_cvt_pk_bf16_f32 v133, v130, v131
	ds_write_b64 v136, v[132:133] offset:25632
	v_add_u32_e32 v136, s87, v138
	v_mov_b64_e32 v[150:151], s[92:93]
	v_mad_u64_u32 v[162:163], s[0:1], v136, s47, v[150:151]
	v_ashrrev_i32_e32 v138, 31, v136
	v_mov_b32_e32 v136, v163
	v_mad_u64_u32 v[164:165], s[0:1], v138, s47, v[136:137]
	v_mov_b32_e32 v163, v164
	v_add_u32_e32 v136, s87, v139
	v_lshl_add_u64 v[162:163], v[162:163], 1, s[96:97]
	v_mad_u64_u32 v[138:139], s[0:1], v136, s47, v[150:151]
	s_waitcnt lgkmcnt(0)
	s_barrier
	ds_read_b128 v[130:133], v140
	v_lshl_add_u64 v[162:163], v[162:163], 0, v[128:129]
	v_ashrrev_i32_e32 v140, 31, v136
	v_mov_b32_e32 v136, v139
	s_waitcnt lgkmcnt(0)
	global_store_dwordx4 v[162:163], v[130:133], off
	s_nop 1
	v_mad_u64_u32 v[162:163], s[0:1], v140, s47, v[136:137]
	v_mov_b32_e32 v139, v162
	v_lshl_add_u64 v[138:139], v[138:139], 1, s[96:97]
	v_lshl_add_u64 v[138:139], v[138:139], 0, v[128:129]
	v_add_u32_e32 v136, s87, v141
	ds_read_b128 v[130:133], v137
	s_waitcnt lgkmcnt(0)
	global_store_dwordx4 v[138:139], v[130:133], off
	s_nop 1
	v_mad_u64_u32 v[138:139], s[0:1], v136, s47, v[150:151]
	v_ashrrev_i32_e32 v140, 31, v136
	v_mov_b32_e32 v136, v139
	v_mad_u64_u32 v[140:141], s[0:1], v140, s47, v[136:137]
	v_mov_b32_e32 v139, v140
	v_lshl_add_u64 v[138:139], v[138:139], 1, s[96:97]
	v_lshl_add_u64 v[138:139], v[138:139], 0, v[128:129]
	v_add_u32_e32 v136, s87, v142
	ds_read_b128 v[130:133], v137 offset:8448
	s_waitcnt lgkmcnt(0)
	global_store_dwordx4 v[138:139], v[130:133], off
	s_nop 1
	v_mad_u64_u32 v[138:139], s[0:1], v136, s47, v[150:151]
	v_ashrrev_i32_e32 v140, 31, v136
	v_mov_b32_e32 v136, v139
	v_mad_u64_u32 v[140:141], s[0:1], v140, s47, v[136:137]
	v_mov_b32_e32 v139, v140
	v_lshl_add_u64 v[138:139], v[138:139], 1, s[96:97]
	v_lshl_add_u64 v[138:139], v[138:139], 0, v[128:129]
	v_add_u32_e32 v136, s87, v143
	ds_read_b128 v[130:133], v137 offset:16896
	s_waitcnt lgkmcnt(0)
	global_store_dwordx4 v[138:139], v[130:133], off
	s_nop 1
	v_mad_u64_u32 v[138:139], s[0:1], v136, s47, v[150:151]
	v_ashrrev_i32_e32 v140, 31, v136
	v_mov_b32_e32 v136, v139
	v_mad_u64_u32 v[140:141], s[0:1], v140, s47, v[136:137]
	v_mov_b32_e32 v139, v140
	v_lshl_add_u64 v[138:139], v[138:139], 1, s[96:97]
	v_lshl_add_u64 v[138:139], v[138:139], 0, v[128:129]
	v_add_u32_e32 v136, s87, v144
	ds_read_b128 v[130:133], v137 offset:25344
	s_waitcnt lgkmcnt(0)
	global_store_dwordx4 v[138:139], v[130:133], off
	s_nop 1
	v_mad_u64_u32 v[138:139], s[0:1], v136, s47, v[150:151]
	v_ashrrev_i32_e32 v140, 31, v136
	v_mov_b32_e32 v136, v139
	v_mad_u64_u32 v[140:141], s[0:1], v140, s47, v[136:137]
	v_mov_b32_e32 v139, v140
	v_lshl_add_u64 v[138:139], v[138:139], 1, s[96:97]
	v_lshl_add_u64 v[138:139], v[138:139], 0, v[128:129]
	v_add_u32_e32 v136, s87, v145
	ds_read_b128 v[130:133], v137 offset:33792
	s_waitcnt lgkmcnt(0)
	global_store_dwordx4 v[138:139], v[130:133], off
	s_nop 1
	v_mad_u64_u32 v[138:139], s[0:1], v136, s47, v[150:151]
	v_ashrrev_i32_e32 v140, 31, v136
	v_mov_b32_e32 v136, v139
	v_mad_u64_u32 v[140:141], s[0:1], v140, s47, v[136:137]
	v_mov_b32_e32 v139, v140
	v_lshl_add_u64 v[138:139], v[138:139], 1, s[96:97]
	ds_read_b128 v[130:133], v137 offset:42240
	v_lshl_add_u64 v[138:139], v[138:139], 0, v[128:129]
	s_waitcnt lgkmcnt(0)
	global_store_dwordx4 v[138:139], v[130:133], off
	s_nop 1
	v_add_u32_e32 v136, s87, v146
	ds_read_b128 v[130:133], v137 offset:50688
	v_ashrrev_i32_e32 v139, 31, v136
	v_mad_u64_u32 v[136:137], s[0:1], v136, s47, v[150:151]
	v_mov_b32_e32 v138, v137
	v_mad_u64_u32 v[138:139], s[0:1], v139, s47, v[138:139]
	v_mov_b32_e32 v137, v138
	v_lshl_add_u64 v[136:137], v[136:137], 1, s[96:97]
	v_lshl_add_u64 v[136:137], v[136:137], 0, v[128:129]
	s_waitcnt lgkmcnt(0)
	global_store_dwordx4 v[136:137], v[130:133], off
	s_nop 1
	s_mov_b64 s[2:3], 0
	s_barrier
